# cache-policy hint: attention output (DIFF) stores marked nt to keep the in-proj output resident for the mixer units
# baseline (speedup 1.0000x reference)
; __device__ __forceinline__ int crow(int r,int hi){return (r&3)+8*(r>>2)+4*hi;}
; __device__ __forceinline__ unsigned cvtpk_s(float lo,float hi){f32x2_t v={lo,hi};bf16x2_t b=__builtin_convertvector(v,bf16x2_t);return __builtin_bit_cast(unsigned,b);}
; template<int THRL> __device__ __forceinline__ void attn_unit(int b,int qb,int T0,const bf16*Q,const bf16*__restrict__ K,const bf16*__restrict__ V,float*Dg,float cs,float lam,char*shm){
;     ...
;   {auto rr=__builtin_amdgcn_permlane32_swap(__float_as_uint(l_reg),__float_as_uint(l_reg),false,false);l_reg=__uint_as_float(rr[0])+__uint_as_float(rr[1]);}
;   if(hi==0)wsf[32+r32]=l_reg;asm volatile("s_waitcnt lgkmcnt(0)":::"memory");
;   float rli[16];
;   #pragma unroll
;   for(int r=0;r<16;++r)rli[r]=__builtin_amdgcn_rcpf(wsf[32+crow(r,hi)]);
;   { typedef __attribute__((address_space(1))) unsigned short gbf16; gbf16*Dw=(gbf16*)Dg+(rowbase+q0+wid*QBLK+4*hi)*768+r32; asm volatile("":"+v"(Dw));
;     #pragma unroll
;     for(int r=0;r<16;++r){
;       #pragma unroll
;       for(int d0=0;d0<4;++d0){ gbf16*p=Dw+((r&3)+8*(r>>2))*768+d0*32; const float v_=o[d0][r]*rli[r]; *p=(unsigned short)cvtpk_s(v_,v_); } } }
.LBB0_304:
	s_or_b64 exec, exec, s[34:35]
	s_waitcnt lgkmcnt(0)
	ds_read_b128 v[2:5], v252 offset:128
	ds_read_b128 v[6:9], v252 offset:160
	ds_read_b128 v[84:87], v252 offset:192
	ds_read_b128 v[88:91], v252 offset:224
	s_add_u32 s22, s96, s52
	s_addc_u32 s23, s97, s53
	s_lshl_b32 s34, s84, 1
	s_add_u32 s22, s22, s34
	s_addc_u32 s23, s23, 0
	v_readfirstlane_b32 s34, v252
	s_lshl_b32 s34, s34, 4
	s_sub_u32 s34, s34, 1103872
	v_lshlrev_b32_e32 v120, 7, v250
	v_lshl_add_u32 v120, v248, 1, v120
	v_add_u32_e32 v120, s34, v120
	v_lshrrev_b32_e32 v122, 3, v240
	v_and_b32_e32 v123, 7, v240
	v_lshlrev_b32_e32 v121, 7, v122
	v_lshl_add_u32 v121, v123, 4, v121
	v_add_u32_e32 v121, s34, v121
	v_or_b32_e32 v122, s79, v122
	v_mov_b64_e32 v[124:125], s[22:23]
	v_mad_i64_i32 v[124:125], s[22:23], v122, s66, v[124:125]
	v_lshlrev_b32_e32 v122, 4, v123
	v_mov_b32_e32 v123, 0
	v_lshl_add_u64 v[124:125], v[124:125], 0, v[122:123]
	s_mov_b64 s[22:23], 0x3000
	v_lshl_add_u64 v[126:127], v[124:125], 0, s[22:23]
	v_lshl_add_u64 v[128:129], v[126:127], 0, s[22:23]
	v_lshl_add_u64 v[130:131], v[128:129], 0, s[22:23]
	s_waitcnt lgkmcnt(0)
	v_rcp_f32_e32 v100, v2
	v_rcp_f32_e32 v101, v3
	v_rcp_f32_e32 v102, v4
	v_rcp_f32_e32 v103, v5
	v_rcp_f32_e32 v104, v6
	v_rcp_f32_e32 v105, v7
	v_rcp_f32_e32 v106, v8
	v_rcp_f32_e32 v107, v9
	v_rcp_f32_e32 v108, v84
	v_rcp_f32_e32 v109, v85
	v_rcp_f32_e32 v110, v86
	v_rcp_f32_e32 v111, v87
	v_rcp_f32_e32 v112, v88
	v_rcp_f32_e32 v113, v89
	v_rcp_f32_e32 v114, v90
	v_rcp_f32_e32 v115, v91
	s_nop 0
	v_mul_f32_e32 v116, v64, v100
	v_mul_f32_e32 v117, v48, v100
	v_cvt_pk_bf16_f32 v116, v116, v117
	ds_write_b16 v120, v116
	ds_write_b16_d16_hi v120, v116 offset:64
	v_mul_f32_e32 v118, v65, v101
	v_mul_f32_e32 v119, v49, v101
	v_cvt_pk_bf16_f32 v118, v118, v119
	ds_write_b16 v120, v118 offset:128
	ds_write_b16_d16_hi v120, v118 offset:192
	v_mul_f32_e32 v116, v66, v102
	v_mul_f32_e32 v117, v50, v102
	v_cvt_pk_bf16_f32 v116, v116, v117
	ds_write_b16 v120, v116 offset:256
	ds_write_b16_d16_hi v120, v116 offset:320
	v_mul_f32_e32 v118, v67, v103
	v_mul_f32_e32 v119, v51, v103
	v_cvt_pk_bf16_f32 v118, v118, v119
	ds_write_b16 v120, v118 offset:384
	ds_write_b16_d16_hi v120, v118 offset:448
	v_mul_f32_e32 v116, v68, v104
	v_mul_f32_e32 v117, v52, v104
	v_cvt_pk_bf16_f32 v116, v116, v117
	ds_write_b16 v120, v116 offset:1024
	ds_write_b16_d16_hi v120, v116 offset:1088
	v_mul_f32_e32 v118, v69, v105
	v_mul_f32_e32 v119, v53, v105
	v_cvt_pk_bf16_f32 v118, v118, v119
	ds_write_b16 v120, v118 offset:1152
	ds_write_b16_d16_hi v120, v118 offset:1216
	v_mul_f32_e32 v116, v70, v106
	v_mul_f32_e32 v117, v54, v106
	v_cvt_pk_bf16_f32 v116, v116, v117
	ds_write_b16 v120, v116 offset:1280
	ds_write_b16_d16_hi v120, v116 offset:1344
	v_mul_f32_e32 v118, v71, v107
	v_mul_f32_e32 v119, v55, v107
	v_cvt_pk_bf16_f32 v118, v118, v119
	ds_write_b16 v120, v118 offset:1408
	ds_write_b16_d16_hi v120, v118 offset:1472
	v_mul_f32_e32 v116, v72, v108
	v_mul_f32_e32 v117, v56, v108
	v_cvt_pk_bf16_f32 v116, v116, v117
	ds_write_b16 v120, v116 offset:2048
	ds_write_b16_d16_hi v120, v116 offset:2112
	v_mul_f32_e32 v118, v73, v109
	v_mul_f32_e32 v119, v57, v109
	v_cvt_pk_bf16_f32 v118, v118, v119
	ds_write_b16 v120, v118 offset:2176
	ds_write_b16_d16_hi v120, v118 offset:2240
	v_mul_f32_e32 v116, v74, v110
	v_mul_f32_e32 v117, v58, v110
	v_cvt_pk_bf16_f32 v116, v116, v117
	ds_write_b16 v120, v116 offset:2304
	ds_write_b16_d16_hi v120, v116 offset:2368
	v_mul_f32_e32 v118, v75, v111
	v_mul_f32_e32 v119, v59, v111
	v_cvt_pk_bf16_f32 v118, v118, v119
	ds_write_b16 v120, v118 offset:2432
	ds_write_b16_d16_hi v120, v118 offset:2496
	v_mul_f32_e32 v116, v76, v112
	v_mul_f32_e32 v117, v60, v112
	v_cvt_pk_bf16_f32 v116, v116, v117
	ds_write_b16 v120, v116 offset:3072
	ds_write_b16_d16_hi v120, v116 offset:3136
	v_mul_f32_e32 v118, v77, v113
	v_mul_f32_e32 v119, v61, v113
	v_cvt_pk_bf16_f32 v118, v118, v119
	ds_write_b16 v120, v118 offset:3200
	ds_write_b16_d16_hi v120, v118 offset:3264
	v_mul_f32_e32 v116, v78, v114
	v_mul_f32_e32 v117, v62, v114
	v_cvt_pk_bf16_f32 v116, v116, v117
	ds_write_b16 v120, v116 offset:3328
	ds_write_b16_d16_hi v120, v116 offset:3392
	v_mul_f32_e32 v118, v79, v115
	v_mul_f32_e32 v119, v63, v115
	v_cvt_pk_bf16_f32 v118, v118, v119
	ds_write_b16 v120, v118 offset:3456
	ds_write_b16_d16_hi v120, v118 offset:3520
	s_waitcnt lgkmcnt(0)
; __device__ __forceinline__ unsigned cvtpk_s(float lo,float hi){f32x2_t v={lo,hi};bf16x2_t b=__builtin_convertvector(v,bf16x2_t);return __builtin_bit_cast(unsigned,b);}
; template<int THRL> __device__ __forceinline__ void attn_unit(int b,int qb,int T0,const bf16*Q,const bf16*__restrict__ K,const bf16*__restrict__ V,float*Dg,float cs,float lam,char*shm){
;     ...
;   { typedef __attribute__((address_space(1))) unsigned short gbf16; gbf16*Dw=(gbf16*)Dg+(rowbase+q0+wid*QBLK+4*hi)*768+r32; asm volatile("":"+v"(Dw));
;     #pragma unroll
;     for(int r=0;r<16;++r){
;       #pragma unroll
;       for(int d0=0;d0<4;++d0){ gbf16*p=Dw+((r&3)+8*(r>>2))*768+d0*32; const float v_=o[d0][r]*rli[r]; *p=(unsigned short)cvtpk_s(v_,v_); } } }
;   asm volatile("s_waitcnt lgkmcnt(0)\n\ts_barrier":::"memory");
	ds_read_b128 v[132:135], v121
	ds_read_b128 v[136:139], v121 offset:1024
	ds_read_b128 v[140:143], v121 offset:2048
	ds_read_b128 v[144:147], v121 offset:3072
	s_waitcnt lgkmcnt(3)
	global_store_dwordx4 v[124:125], v[132:135], off nt
	s_waitcnt lgkmcnt(2)
	global_store_dwordx4 v[126:127], v[136:139], off nt
	s_waitcnt lgkmcnt(1)
	global_store_dwordx4 v[128:129], v[140:143], off nt
	s_waitcnt lgkmcnt(0)
	global_store_dwordx4 v[130:131], v[144:147], off nt
	v_mul_f32_e32 v116, v32, v100
	v_mul_f32_e32 v117, v16, v100
	v_cvt_pk_bf16_f32 v116, v116, v117
	ds_write_b16 v120, v116
	ds_write_b16_d16_hi v120, v116 offset:64
	v_mul_f32_e32 v118, v33, v101
	v_mul_f32_e32 v119, v17, v101
	v_cvt_pk_bf16_f32 v118, v118, v119
	ds_write_b16 v120, v118 offset:128
	ds_write_b16_d16_hi v120, v118 offset:192
	v_mul_f32_e32 v116, v34, v102
	v_mul_f32_e32 v117, v18, v102
	v_cvt_pk_bf16_f32 v116, v116, v117
	ds_write_b16 v120, v116 offset:256
	ds_write_b16_d16_hi v120, v116 offset:320
	v_mul_f32_e32 v118, v35, v103
	v_mul_f32_e32 v119, v19, v103
	v_cvt_pk_bf16_f32 v118, v118, v119
	ds_write_b16 v120, v118 offset:384
	ds_write_b16_d16_hi v120, v118 offset:448
	v_mul_f32_e32 v116, v36, v104
	v_mul_f32_e32 v117, v20, v104
	v_cvt_pk_bf16_f32 v116, v116, v117
	ds_write_b16 v120, v116 offset:1024
	ds_write_b16_d16_hi v120, v116 offset:1088
	v_mul_f32_e32 v118, v37, v105
	v_mul_f32_e32 v119, v21, v105
	v_cvt_pk_bf16_f32 v118, v118, v119
	ds_write_b16 v120, v118 offset:1152
	ds_write_b16_d16_hi v120, v118 offset:1216
	v_mul_f32_e32 v116, v38, v106
	v_mul_f32_e32 v117, v22, v106
	v_cvt_pk_bf16_f32 v116, v116, v117
	ds_write_b16 v120, v116 offset:1280
	ds_write_b16_d16_hi v120, v116 offset:1344
	v_mul_f32_e32 v118, v39, v107
	v_mul_f32_e32 v119, v23, v107
	v_cvt_pk_bf16_f32 v118, v118, v119
	ds_write_b16 v120, v118 offset:1408
	ds_write_b16_d16_hi v120, v118 offset:1472
	v_mul_f32_e32 v116, v40, v108
	v_mul_f32_e32 v117, v24, v108
	v_cvt_pk_bf16_f32 v116, v116, v117
	ds_write_b16 v120, v116 offset:2048
	ds_write_b16_d16_hi v120, v116 offset:2112
	v_mul_f32_e32 v118, v41, v109
	v_mul_f32_e32 v119, v25, v109
	v_cvt_pk_bf16_f32 v118, v118, v119
	ds_write_b16 v120, v118 offset:2176
	ds_write_b16_d16_hi v120, v118 offset:2240
	v_mul_f32_e32 v116, v42, v110
	v_mul_f32_e32 v117, v26, v110
	v_cvt_pk_bf16_f32 v116, v116, v117
	ds_write_b16 v120, v116 offset:2304
	ds_write_b16_d16_hi v120, v116 offset:2368
	v_mul_f32_e32 v118, v43, v111
	v_mul_f32_e32 v119, v27, v111
	v_cvt_pk_bf16_f32 v118, v118, v119
	ds_write_b16 v120, v118 offset:2432
	ds_write_b16_d16_hi v120, v118 offset:2496
	v_mul_f32_e32 v116, v44, v112
	v_mul_f32_e32 v117, v28, v112
	v_cvt_pk_bf16_f32 v116, v116, v117
	ds_write_b16 v120, v116 offset:3072
	ds_write_b16_d16_hi v120, v116 offset:3136
	v_mul_f32_e32 v118, v45, v113
	v_mul_f32_e32 v119, v29, v113
	v_cvt_pk_bf16_f32 v118, v118, v119
	ds_write_b16 v120, v118 offset:3200
	ds_write_b16_d16_hi v120, v118 offset:3264
	v_mul_f32_e32 v116, v46, v114
	v_mul_f32_e32 v117, v30, v114
	v_cvt_pk_bf16_f32 v116, v116, v117
	ds_write_b16 v120, v116 offset:3328
	ds_write_b16_d16_hi v120, v116 offset:3392
	v_mul_f32_e32 v118, v47, v115
	v_mul_f32_e32 v119, v31, v115
	v_cvt_pk_bf16_f32 v118, v118, v119
	ds_write_b16 v120, v118 offset:3456
	ds_write_b16_d16_hi v120, v118 offset:3520
	s_waitcnt lgkmcnt(0)
	ds_read_b128 v[132:135], v121
	ds_read_b128 v[136:139], v121 offset:1024
	ds_read_b128 v[140:143], v121 offset:2048
	ds_read_b128 v[144:147], v121 offset:3072
	s_waitcnt lgkmcnt(3)
	global_store_dwordx4 v[124:125], v[132:135], off offset:128 nt
	s_waitcnt lgkmcnt(2)
	global_store_dwordx4 v[126:127], v[136:139], off offset:128 nt
	s_waitcnt lgkmcnt(1)
	global_store_dwordx4 v[128:129], v[140:143], off offset:128 nt
	s_waitcnt lgkmcnt(0)
	global_store_dwordx4 v[130:131], v[144:147], off offset:128 nt
	s_waitcnt lgkmcnt(0)
	s_barrier
	s_mov_b64 s[44:45], 0
